# M-merge epilogue: 16 gate loads issued up front, counted vmcnt(15), instead of load/vmcnt(0)/store ladder
# speedup vs baseline: 1.0077x; 1.0077x over previous
; __device__ __forceinline__ unsigned pk2(float lo, float hi) { f32x2 v = {lo, hi}; bf16x2_t b = __builtin_convertvector(v, bf16x2_t); return __builtin_bit_cast(unsigned, b); }
;     __device__ __forceinline__ void operator()(const f32x4 (&acc)[2][2][4][2], const Unit& u, int wr, int wc, int fr, int fq) const {
;         const int row0 = u.pm * 256 + wr * 64 + fr, col0 = u.pn * 256 + wc * 32 + 8 * fq;
; #pragma unroll
;         for (int ai = 0; ai < 2; ++ai)
; #pragma unroll
;             for (int m = 0; m < 4; ++m) {
;                 const size_t row = (size_t)(row0 + ai * 128 + m * 16);
; #pragma unroll
;                 for (int bj = 0; bj < 2; ++bj) {
;                     const int col = col0 + bj * 128;
;                     const u32x4 g = *(const u32x4*)(P + row * PS + C_GATE + 4096 + col);
;                     f32x4 v0 = acc[ai][bj][m][0], v1 = acc[ai][bj][m][1];
;                     v0[0] *= fmaxf(bflo(g.x), 1e-20f); v0[1] *= fmaxf(bfhi(g.x), 1e-20f); v0[2] *= fmaxf(bflo(g.y), 1e-20f); v0[3] *= fmaxf(bfhi(g.y), 1e-20f);
;                     v1[0] *= fmaxf(bflo(g.z), 1e-20f); v1[1] *= fmaxf(bfhi(g.z), 1e-20f); v1[2] *= fmaxf(bflo(g.w), 1e-20f); v1[3] *= fmaxf(bfhi(g.w), 1e-20f);
;                     u32x4 w; w.x = pk2(v0[0], v0[1]); w.y = pk2(v0[2], v0[3]); w.z = pk2(v1[0], v1[1]); w.w = pk2(v1[2], v1[3]);
;                     *(u32x4*)(Yb + row * DM + col) = w;
.LBB0_766:
	v_lshl_add_u32 v34, s18, 8, v174
	v_mov_b64_e32 v[36:37], s[42:43]
	v_ashrrev_i32_e32 v159, 31, v158
	v_mad_i64_i32 v[36:37], vcc, v34, s90, v[36:37]
	v_lshlrev_b64 v[160:161], 1, v[158:159]
	v_lshl_add_u64 v[36:37], v[36:37], 0, s[36:37]
	v_mov_b32_e32 v164, v34
	v_ashrrev_i32_e32 v165, 31, v34
	v_lshl_add_u64 v[36:37], v[36:37], 0, v[160:161]
	v_lshlrev_b64 v[164:165], 12, v[164:165]
	v_lshl_add_u64 v[162:163], s[40:41], 0, v[164:165]
	v_lshl_add_u64 v[162:163], v[162:163], 0, v[160:161]
	s_mov_b32 s4, 0x60000
	s_mov_b32 s5, 0
	global_load_dwordx4 v[134:137], v[36:37], off
	global_load_dwordx4 v[138:141], v[36:37], off offset:256
	v_lshl_add_u64 v[36:37], v[36:37], 0, s[4:5]
	global_load_dwordx4 v[178:181], v[36:37], off
	global_load_dwordx4 v[182:185], v[36:37], off offset:256
	v_lshl_add_u64 v[36:37], v[36:37], 0, s[4:5]
	global_load_dwordx4 v[186:189], v[36:37], off
	global_load_dwordx4 v[190:193], v[36:37], off offset:256
	v_lshl_add_u64 v[36:37], v[36:37], 0, s[4:5]
	global_load_dwordx4 v[194:197], v[36:37], off
	global_load_dwordx4 v[198:201], v[36:37], off offset:256
	s_mov_b32 s4, 0x1e0000
	v_lshl_add_u64 v[36:37], v[36:37], 0, s[4:5]
	s_mov_b32 s4, 0x60000
	global_load_dwordx4 v[202:205], v[36:37], off
	global_load_dwordx4 v[206:209], v[36:37], off offset:256
	v_lshl_add_u64 v[36:37], v[36:37], 0, s[4:5]
	global_load_dwordx4 v[210:213], v[36:37], off
	global_load_dwordx4 v[214:217], v[36:37], off offset:256
	v_lshl_add_u64 v[36:37], v[36:37], 0, s[4:5]
	global_load_dwordx4 v[218:221], v[36:37], off
	global_load_dwordx4 v[222:225], v[36:37], off offset:256
	v_lshl_add_u64 v[36:37], v[36:37], 0, s[4:5]
	global_load_dwordx4 v[226:229], v[36:37], off
	global_load_dwordx4 v[230:233], v[36:37], off offset:256
	s_mov_b32 s4, 0x10000
	s_waitcnt vmcnt(15)
	v_lshlrev_b32_e32 v246, 16, v134
	v_and_b32_e32 v247, 0xffff0000, v134
	v_lshlrev_b32_e32 v248, 16, v135
	v_and_b32_e32 v249, 0xffff0000, v135
	v_max_f32_e32 v246, v246, v246
	v_max_f32_e32 v247, v247, v247
	v_max_f32_e32 v248, v248, v248
	v_max_f32_e32 v249, v249, v249
	v_max_f32_e32 v246, 0x1e3ce508, v246
	v_max_f32_e32 v247, 0x1e3ce508, v247
	v_max_f32_e32 v248, 0x1e3ce508, v248
	v_max_f32_e32 v249, 0x1e3ce508, v249
	v_pk_mul_f32 v[130:131], v[130:131], v[246:247]
	v_pk_mul_f32 v[132:133], v[132:133], v[248:249]
	v_lshlrev_b32_e32 v246, 16, v136
	v_and_b32_e32 v247, 0xffff0000, v136
	v_lshlrev_b32_e32 v248, 16, v137
	v_and_b32_e32 v249, 0xffff0000, v137
	v_max_f32_e32 v246, v246, v246
	v_max_f32_e32 v247, v247, v247
	v_max_f32_e32 v248, v248, v248
	v_max_f32_e32 v249, v249, v249
	v_max_f32_e32 v246, 0x1e3ce508, v246
	v_max_f32_e32 v247, 0x1e3ce508, v247
	v_max_f32_e32 v248, 0x1e3ce508, v248
	v_max_f32_e32 v249, 0x1e3ce508, v249
	v_pk_mul_f32 v[126:127], v[126:127], v[246:247]
	v_pk_mul_f32 v[128:129], v[128:129], v[248:249]
	v_cvt_pk_bf16_f32 v134, v130, v131
	v_cvt_pk_bf16_f32 v135, v132, v133
	v_cvt_pk_bf16_f32 v136, v126, v127
	v_cvt_pk_bf16_f32 v137, v128, v129
	global_store_dwordx4 v[162:163], v[134:137], off
	s_waitcnt vmcnt(15)
	v_lshlrev_b32_e32 v246, 16, v138
	v_and_b32_e32 v247, 0xffff0000, v138
	v_lshlrev_b32_e32 v248, 16, v139
	v_and_b32_e32 v249, 0xffff0000, v139
	v_max_f32_e32 v246, v246, v246
	v_max_f32_e32 v247, v247, v247
	v_max_f32_e32 v248, v248, v248
	v_max_f32_e32 v249, v249, v249
	v_max_f32_e32 v246, 0x1e3ce508, v246
	v_max_f32_e32 v247, 0x1e3ce508, v247
	v_max_f32_e32 v248, 0x1e3ce508, v248
	v_max_f32_e32 v249, 0x1e3ce508, v249
	v_pk_mul_f32 v[122:123], v[122:123], v[246:247]
	v_pk_mul_f32 v[124:125], v[124:125], v[248:249]
	v_lshlrev_b32_e32 v246, 16, v140
	v_and_b32_e32 v247, 0xffff0000, v140
	v_lshlrev_b32_e32 v248, 16, v141
	v_and_b32_e32 v249, 0xffff0000, v141
	v_max_f32_e32 v246, v246, v246
	v_max_f32_e32 v247, v247, v247
	v_max_f32_e32 v248, v248, v248
	v_max_f32_e32 v249, v249, v249
	v_max_f32_e32 v246, 0x1e3ce508, v246
	v_max_f32_e32 v247, 0x1e3ce508, v247
	v_max_f32_e32 v248, 0x1e3ce508, v248
	v_max_f32_e32 v249, 0x1e3ce508, v249
	v_pk_mul_f32 v[118:119], v[118:119], v[246:247]
	v_pk_mul_f32 v[120:121], v[120:121], v[248:249]
	v_cvt_pk_bf16_f32 v138, v122, v123
	v_cvt_pk_bf16_f32 v139, v124, v125
	v_cvt_pk_bf16_f32 v140, v118, v119
	v_cvt_pk_bf16_f32 v141, v120, v121
	global_store_dwordx4 v[162:163], v[138:141], off offset:256
	v_lshl_add_u64 v[162:163], v[162:163], 0, s[4:5]
	s_waitcnt vmcnt(15)
	v_lshlrev_b32_e32 v246, 16, v178
	v_and_b32_e32 v247, 0xffff0000, v178
	v_lshlrev_b32_e32 v248, 16, v179
	v_and_b32_e32 v249, 0xffff0000, v179
	v_max_f32_e32 v246, v246, v246
	v_max_f32_e32 v247, v247, v247
	v_max_f32_e32 v248, v248, v248
	v_max_f32_e32 v249, v249, v249
	v_max_f32_e32 v246, 0x1e3ce508, v246
	v_max_f32_e32 v247, 0x1e3ce508, v247
	v_max_f32_e32 v248, 0x1e3ce508, v248
	v_max_f32_e32 v249, 0x1e3ce508, v249
	v_pk_mul_f32 v[114:115], v[114:115], v[246:247]
	v_pk_mul_f32 v[116:117], v[116:117], v[248:249]
	v_lshlrev_b32_e32 v246, 16, v180
	v_and_b32_e32 v247, 0xffff0000, v180
	v_lshlrev_b32_e32 v248, 16, v181
	v_and_b32_e32 v249, 0xffff0000, v181
	v_max_f32_e32 v246, v246, v246
	v_max_f32_e32 v247, v247, v247
	v_max_f32_e32 v248, v248, v248
	v_max_f32_e32 v249, v249, v249
	v_max_f32_e32 v246, 0x1e3ce508, v246
	v_max_f32_e32 v247, 0x1e3ce508, v247
	v_max_f32_e32 v248, 0x1e3ce508, v248
	v_max_f32_e32 v249, 0x1e3ce508, v249
	v_pk_mul_f32 v[110:111], v[110:111], v[246:247]
	v_pk_mul_f32 v[112:113], v[112:113], v[248:249]
	v_cvt_pk_bf16_f32 v178, v114, v115
	v_cvt_pk_bf16_f32 v179, v116, v117
	v_cvt_pk_bf16_f32 v180, v110, v111
	v_cvt_pk_bf16_f32 v181, v112, v113
	global_store_dwordx4 v[162:163], v[178:181], off
	s_waitcnt vmcnt(15)
; __device__ __forceinline__ unsigned pk2(float lo, float hi) { f32x2 v = {lo, hi}; bf16x2_t b = __builtin_convertvector(v, bf16x2_t); return __builtin_bit_cast(unsigned, b); }
;     __device__ __forceinline__ void operator()(const f32x4 (&acc)[2][2][4][2], const Unit& u, int wr, int wc, int fr, int fq) const {
;     ...
;                 for (int bj = 0; bj < 2; ++bj) {
;                     const int col = col0 + bj * 128;
;                     const u32x4 g = *(const u32x4*)(P + row * PS + C_GATE + 4096 + col);
;                     f32x4 v0 = acc[ai][bj][m][0], v1 = acc[ai][bj][m][1];
;                     v0[0] *= fmaxf(bflo(g.x), 1e-20f); v0[1] *= fmaxf(bfhi(g.x), 1e-20f); v0[2] *= fmaxf(bflo(g.y), 1e-20f); v0[3] *= fmaxf(bfhi(g.y), 1e-20f);
;                     v1[0] *= fmaxf(bflo(g.z), 1e-20f); v1[1] *= fmaxf(bfhi(g.z), 1e-20f); v1[2] *= fmaxf(bflo(g.w), 1e-20f); v1[3] *= fmaxf(bfhi(g.w), 1e-20f);
;                     u32x4 w; w.x = pk2(v0[0], v0[1]); w.y = pk2(v0[2], v0[3]); w.z = pk2(v1[0], v1[1]); w.w = pk2(v1[2], v1[3]);
;                     *(u32x4*)(Yb + row * DM + col) = w;
	v_lshlrev_b32_e32 v246, 16, v182
	v_and_b32_e32 v247, 0xffff0000, v182
	v_lshlrev_b32_e32 v248, 16, v183
	v_and_b32_e32 v249, 0xffff0000, v183
	v_max_f32_e32 v246, v246, v246
	v_max_f32_e32 v247, v247, v247
	v_max_f32_e32 v248, v248, v248
	v_max_f32_e32 v249, v249, v249
	v_max_f32_e32 v246, 0x1e3ce508, v246
	v_max_f32_e32 v247, 0x1e3ce508, v247
	v_max_f32_e32 v248, 0x1e3ce508, v248
	v_max_f32_e32 v249, 0x1e3ce508, v249
	v_pk_mul_f32 v[106:107], v[106:107], v[246:247]
	v_pk_mul_f32 v[108:109], v[108:109], v[248:249]
	v_lshlrev_b32_e32 v246, 16, v184
	v_and_b32_e32 v247, 0xffff0000, v184
	v_lshlrev_b32_e32 v248, 16, v185
	v_and_b32_e32 v249, 0xffff0000, v185
	v_max_f32_e32 v246, v246, v246
	v_max_f32_e32 v247, v247, v247
	v_max_f32_e32 v248, v248, v248
	v_max_f32_e32 v249, v249, v249
	v_max_f32_e32 v246, 0x1e3ce508, v246
	v_max_f32_e32 v247, 0x1e3ce508, v247
	v_max_f32_e32 v248, 0x1e3ce508, v248
	v_max_f32_e32 v249, 0x1e3ce508, v249
	v_pk_mul_f32 v[102:103], v[102:103], v[246:247]
	v_pk_mul_f32 v[104:105], v[104:105], v[248:249]
	v_cvt_pk_bf16_f32 v182, v106, v107
	v_cvt_pk_bf16_f32 v183, v108, v109
	v_cvt_pk_bf16_f32 v184, v102, v103
	v_cvt_pk_bf16_f32 v185, v104, v105
	global_store_dwordx4 v[162:163], v[182:185], off offset:256
	v_lshl_add_u64 v[162:163], v[162:163], 0, s[4:5]
	s_waitcnt vmcnt(15)
	v_lshlrev_b32_e32 v246, 16, v186
	v_and_b32_e32 v247, 0xffff0000, v186
	v_lshlrev_b32_e32 v248, 16, v187
	v_and_b32_e32 v249, 0xffff0000, v187
	v_max_f32_e32 v246, v246, v246
	v_max_f32_e32 v247, v247, v247
	v_max_f32_e32 v248, v248, v248
	v_max_f32_e32 v249, v249, v249
	v_max_f32_e32 v246, 0x1e3ce508, v246
	v_max_f32_e32 v247, 0x1e3ce508, v247
	v_max_f32_e32 v248, 0x1e3ce508, v248
	v_max_f32_e32 v249, 0x1e3ce508, v249
	v_pk_mul_f32 v[98:99], v[98:99], v[246:247]
	v_pk_mul_f32 v[100:101], v[100:101], v[248:249]
	v_lshlrev_b32_e32 v246, 16, v188
	v_and_b32_e32 v247, 0xffff0000, v188
	v_lshlrev_b32_e32 v248, 16, v189
	v_and_b32_e32 v249, 0xffff0000, v189
	v_max_f32_e32 v246, v246, v246
	v_max_f32_e32 v247, v247, v247
	v_max_f32_e32 v248, v248, v248
	v_max_f32_e32 v249, v249, v249
	v_max_f32_e32 v246, 0x1e3ce508, v246
	v_max_f32_e32 v247, 0x1e3ce508, v247
	v_max_f32_e32 v248, 0x1e3ce508, v248
	v_max_f32_e32 v249, 0x1e3ce508, v249
	v_pk_mul_f32 v[94:95], v[94:95], v[246:247]
	v_pk_mul_f32 v[96:97], v[96:97], v[248:249]
	v_cvt_pk_bf16_f32 v186, v98, v99
	v_cvt_pk_bf16_f32 v187, v100, v101
	v_cvt_pk_bf16_f32 v188, v94, v95
	v_cvt_pk_bf16_f32 v189, v96, v97
	global_store_dwordx4 v[162:163], v[186:189], off
	s_waitcnt vmcnt(15)
	v_lshlrev_b32_e32 v246, 16, v190
	v_and_b32_e32 v247, 0xffff0000, v190
	v_lshlrev_b32_e32 v248, 16, v191
	v_and_b32_e32 v249, 0xffff0000, v191
	v_max_f32_e32 v246, v246, v246
	v_max_f32_e32 v247, v247, v247
	v_max_f32_e32 v248, v248, v248
	v_max_f32_e32 v249, v249, v249
	v_max_f32_e32 v246, 0x1e3ce508, v246
	v_max_f32_e32 v247, 0x1e3ce508, v247
	v_max_f32_e32 v248, 0x1e3ce508, v248
	v_max_f32_e32 v249, 0x1e3ce508, v249
	v_pk_mul_f32 v[90:91], v[90:91], v[246:247]
	v_pk_mul_f32 v[92:93], v[92:93], v[248:249]
	v_lshlrev_b32_e32 v246, 16, v192
	v_and_b32_e32 v247, 0xffff0000, v192
	v_lshlrev_b32_e32 v248, 16, v193
	v_and_b32_e32 v249, 0xffff0000, v193
	v_max_f32_e32 v246, v246, v246
	v_max_f32_e32 v247, v247, v247
	v_max_f32_e32 v248, v248, v248
	v_max_f32_e32 v249, v249, v249
	v_max_f32_e32 v246, 0x1e3ce508, v246
	v_max_f32_e32 v247, 0x1e3ce508, v247
	v_max_f32_e32 v248, 0x1e3ce508, v248
	v_max_f32_e32 v249, 0x1e3ce508, v249
	v_pk_mul_f32 v[86:87], v[86:87], v[246:247]
	v_pk_mul_f32 v[88:89], v[88:89], v[248:249]
	v_cvt_pk_bf16_f32 v190, v90, v91
	v_cvt_pk_bf16_f32 v191, v92, v93
	v_cvt_pk_bf16_f32 v192, v86, v87
	v_cvt_pk_bf16_f32 v193, v88, v89
	global_store_dwordx4 v[162:163], v[190:193], off offset:256
	v_lshl_add_u64 v[162:163], v[162:163], 0, s[4:5]
	s_waitcnt vmcnt(15)
	v_lshlrev_b32_e32 v246, 16, v194
	v_and_b32_e32 v247, 0xffff0000, v194
	v_lshlrev_b32_e32 v248, 16, v195
	v_and_b32_e32 v249, 0xffff0000, v195
	v_max_f32_e32 v246, v246, v246
	v_max_f32_e32 v247, v247, v247
	v_max_f32_e32 v248, v248, v248
	v_max_f32_e32 v249, v249, v249
	v_max_f32_e32 v246, 0x1e3ce508, v246
	v_max_f32_e32 v247, 0x1e3ce508, v247
	v_max_f32_e32 v248, 0x1e3ce508, v248
	v_max_f32_e32 v249, 0x1e3ce508, v249
	v_pk_mul_f32 v[82:83], v[82:83], v[246:247]
	v_pk_mul_f32 v[84:85], v[84:85], v[248:249]
	v_lshlrev_b32_e32 v246, 16, v196
	v_and_b32_e32 v247, 0xffff0000, v196
	v_lshlrev_b32_e32 v248, 16, v197
	v_and_b32_e32 v249, 0xffff0000, v197
	v_max_f32_e32 v246, v246, v246
	v_max_f32_e32 v247, v247, v247
	v_max_f32_e32 v248, v248, v248
	v_max_f32_e32 v249, v249, v249
	v_max_f32_e32 v246, 0x1e3ce508, v246
	v_max_f32_e32 v247, 0x1e3ce508, v247
	v_max_f32_e32 v248, 0x1e3ce508, v248
	v_max_f32_e32 v249, 0x1e3ce508, v249
	v_pk_mul_f32 v[78:79], v[78:79], v[246:247]
	v_pk_mul_f32 v[80:81], v[80:81], v[248:249]
	v_cvt_pk_bf16_f32 v194, v82, v83
	v_cvt_pk_bf16_f32 v195, v84, v85
	v_cvt_pk_bf16_f32 v196, v78, v79
	v_cvt_pk_bf16_f32 v197, v80, v81
	global_store_dwordx4 v[162:163], v[194:197], off
	s_waitcnt vmcnt(15)
; __device__ __forceinline__ unsigned pk2(float lo, float hi) { f32x2 v = {lo, hi}; bf16x2_t b = __builtin_convertvector(v, bf16x2_t); return __builtin_bit_cast(unsigned, b); }
;     __device__ __forceinline__ void operator()(const f32x4 (&acc)[2][2][4][2], const Unit& u, int wr, int wc, int fr, int fq) const {
;     ...
;                 for (int bj = 0; bj < 2; ++bj) {
;                     const int col = col0 + bj * 128;
;                     const u32x4 g = *(const u32x4*)(P + row * PS + C_GATE + 4096 + col);
;                     f32x4 v0 = acc[ai][bj][m][0], v1 = acc[ai][bj][m][1];
;                     v0[0] *= fmaxf(bflo(g.x), 1e-20f); v0[1] *= fmaxf(bfhi(g.x), 1e-20f); v0[2] *= fmaxf(bflo(g.y), 1e-20f); v0[3] *= fmaxf(bfhi(g.y), 1e-20f);
;                     v1[0] *= fmaxf(bflo(g.z), 1e-20f); v1[1] *= fmaxf(bfhi(g.z), 1e-20f); v1[2] *= fmaxf(bflo(g.w), 1e-20f); v1[3] *= fmaxf(bfhi(g.w), 1e-20f);
;                     u32x4 w; w.x = pk2(v0[0], v0[1]); w.y = pk2(v0[2], v0[3]); w.z = pk2(v1[0], v1[1]); w.w = pk2(v1[2], v1[3]);
;                     *(u32x4*)(Yb + row * DM + col) = w;
	v_lshlrev_b32_e32 v246, 16, v198
	v_and_b32_e32 v247, 0xffff0000, v198
	v_lshlrev_b32_e32 v248, 16, v199
	v_and_b32_e32 v249, 0xffff0000, v199
	v_max_f32_e32 v246, v246, v246
	v_max_f32_e32 v247, v247, v247
	v_max_f32_e32 v248, v248, v248
	v_max_f32_e32 v249, v249, v249
	v_max_f32_e32 v246, 0x1e3ce508, v246
	v_max_f32_e32 v247, 0x1e3ce508, v247
	v_max_f32_e32 v248, 0x1e3ce508, v248
	v_max_f32_e32 v249, 0x1e3ce508, v249
	v_pk_mul_f32 v[74:75], v[74:75], v[246:247]
	v_pk_mul_f32 v[76:77], v[76:77], v[248:249]
	v_lshlrev_b32_e32 v246, 16, v200
	v_and_b32_e32 v247, 0xffff0000, v200
	v_lshlrev_b32_e32 v248, 16, v201
	v_and_b32_e32 v249, 0xffff0000, v201
	v_max_f32_e32 v246, v246, v246
	v_max_f32_e32 v247, v247, v247
	v_max_f32_e32 v248, v248, v248
	v_max_f32_e32 v249, v249, v249
	v_max_f32_e32 v246, 0x1e3ce508, v246
	v_max_f32_e32 v247, 0x1e3ce508, v247
	v_max_f32_e32 v248, 0x1e3ce508, v248
	v_max_f32_e32 v249, 0x1e3ce508, v249
	v_pk_mul_f32 v[70:71], v[70:71], v[246:247]
	v_pk_mul_f32 v[72:73], v[72:73], v[248:249]
	v_cvt_pk_bf16_f32 v198, v74, v75
	v_cvt_pk_bf16_f32 v199, v76, v77
	v_cvt_pk_bf16_f32 v200, v70, v71
	v_cvt_pk_bf16_f32 v201, v72, v73
	global_store_dwordx4 v[162:163], v[198:201], off offset:256
	s_mov_b32 s4, 0x50000
	v_lshl_add_u64 v[162:163], v[162:163], 0, s[4:5]
	s_mov_b32 s4, 0x10000
	s_waitcnt vmcnt(15)
	v_lshlrev_b32_e32 v246, 16, v202
	v_and_b32_e32 v247, 0xffff0000, v202
	v_lshlrev_b32_e32 v248, 16, v203
	v_and_b32_e32 v249, 0xffff0000, v203
	v_max_f32_e32 v246, v246, v246
	v_max_f32_e32 v247, v247, v247
	v_max_f32_e32 v248, v248, v248
	v_max_f32_e32 v249, v249, v249
	v_max_f32_e32 v246, 0x1e3ce508, v246
	v_max_f32_e32 v247, 0x1e3ce508, v247
	v_max_f32_e32 v248, 0x1e3ce508, v248
	v_max_f32_e32 v249, 0x1e3ce508, v249
	v_pk_mul_f32 v[66:67], v[66:67], v[246:247]
	v_pk_mul_f32 v[68:69], v[68:69], v[248:249]
	v_lshlrev_b32_e32 v246, 16, v204
	v_and_b32_e32 v247, 0xffff0000, v204
	v_lshlrev_b32_e32 v248, 16, v205
	v_and_b32_e32 v249, 0xffff0000, v205
	v_max_f32_e32 v246, v246, v246
	v_max_f32_e32 v247, v247, v247
	v_max_f32_e32 v248, v248, v248
	v_max_f32_e32 v249, v249, v249
	v_max_f32_e32 v246, 0x1e3ce508, v246
	v_max_f32_e32 v247, 0x1e3ce508, v247
	v_max_f32_e32 v248, 0x1e3ce508, v248
	v_max_f32_e32 v249, 0x1e3ce508, v249
	v_pk_mul_f32 v[62:63], v[62:63], v[246:247]
	v_pk_mul_f32 v[64:65], v[64:65], v[248:249]
	v_cvt_pk_bf16_f32 v202, v66, v67
	v_cvt_pk_bf16_f32 v203, v68, v69
	v_cvt_pk_bf16_f32 v204, v62, v63
	v_cvt_pk_bf16_f32 v205, v64, v65
	global_store_dwordx4 v[162:163], v[202:205], off
	s_waitcnt vmcnt(15)
	v_lshlrev_b32_e32 v246, 16, v206
	v_and_b32_e32 v247, 0xffff0000, v206
	v_lshlrev_b32_e32 v248, 16, v207
	v_and_b32_e32 v249, 0xffff0000, v207
	v_max_f32_e32 v246, v246, v246
	v_max_f32_e32 v247, v247, v247
	v_max_f32_e32 v248, v248, v248
	v_max_f32_e32 v249, v249, v249
	v_max_f32_e32 v246, 0x1e3ce508, v246
	v_max_f32_e32 v247, 0x1e3ce508, v247
	v_max_f32_e32 v248, 0x1e3ce508, v248
	v_max_f32_e32 v249, 0x1e3ce508, v249
	v_pk_mul_f32 v[58:59], v[58:59], v[246:247]
	v_pk_mul_f32 v[60:61], v[60:61], v[248:249]
	v_lshlrev_b32_e32 v246, 16, v208
	v_and_b32_e32 v247, 0xffff0000, v208
	v_lshlrev_b32_e32 v248, 16, v209
	v_and_b32_e32 v249, 0xffff0000, v209
	v_max_f32_e32 v246, v246, v246
	v_max_f32_e32 v247, v247, v247
	v_max_f32_e32 v248, v248, v248
	v_max_f32_e32 v249, v249, v249
	v_max_f32_e32 v246, 0x1e3ce508, v246
	v_max_f32_e32 v247, 0x1e3ce508, v247
	v_max_f32_e32 v248, 0x1e3ce508, v248
	v_max_f32_e32 v249, 0x1e3ce508, v249
	v_pk_mul_f32 v[54:55], v[54:55], v[246:247]
	v_pk_mul_f32 v[56:57], v[56:57], v[248:249]
	v_cvt_pk_bf16_f32 v206, v58, v59
	v_cvt_pk_bf16_f32 v207, v60, v61
	v_cvt_pk_bf16_f32 v208, v54, v55
	v_cvt_pk_bf16_f32 v209, v56, v57
	global_store_dwordx4 v[162:163], v[206:209], off offset:256
	v_lshl_add_u64 v[162:163], v[162:163], 0, s[4:5]
	s_waitcnt vmcnt(15)
	v_lshlrev_b32_e32 v246, 16, v210
	v_and_b32_e32 v247, 0xffff0000, v210
	v_lshlrev_b32_e32 v248, 16, v211
	v_and_b32_e32 v249, 0xffff0000, v211
	v_max_f32_e32 v246, v246, v246
	v_max_f32_e32 v247, v247, v247
	v_max_f32_e32 v248, v248, v248
	v_max_f32_e32 v249, v249, v249
	v_max_f32_e32 v246, 0x1e3ce508, v246
	v_max_f32_e32 v247, 0x1e3ce508, v247
	v_max_f32_e32 v248, 0x1e3ce508, v248
	v_max_f32_e32 v249, 0x1e3ce508, v249
	v_pk_mul_f32 v[50:51], v[50:51], v[246:247]
	v_pk_mul_f32 v[52:53], v[52:53], v[248:249]
	v_lshlrev_b32_e32 v246, 16, v212
	v_and_b32_e32 v247, 0xffff0000, v212
	v_lshlrev_b32_e32 v248, 16, v213
	v_and_b32_e32 v249, 0xffff0000, v213
	v_max_f32_e32 v246, v246, v246
	v_max_f32_e32 v247, v247, v247
	v_max_f32_e32 v248, v248, v248
	v_max_f32_e32 v249, v249, v249
	v_max_f32_e32 v246, 0x1e3ce508, v246
	v_max_f32_e32 v247, 0x1e3ce508, v247
	v_max_f32_e32 v248, 0x1e3ce508, v248
	v_max_f32_e32 v249, 0x1e3ce508, v249
	v_pk_mul_f32 v[46:47], v[46:47], v[246:247]
	v_pk_mul_f32 v[48:49], v[48:49], v[248:249]
	v_cvt_pk_bf16_f32 v210, v50, v51
	v_cvt_pk_bf16_f32 v211, v52, v53
	v_cvt_pk_bf16_f32 v212, v46, v47
	v_cvt_pk_bf16_f32 v213, v48, v49
	global_store_dwordx4 v[162:163], v[210:213], off
	s_waitcnt vmcnt(15)
; #define PG8_BAR __builtin_amdgcn_s_barrier()
; __device__ __forceinline__ unsigned pk2(float lo, float hi) { f32x2 v = {lo, hi}; bf16x2_t b = __builtin_convertvector(v, bf16x2_t); return __builtin_bit_cast(unsigned, b); }
; template <class Epi, class Sched, bool ALIGN_EPI = false, bool SP2 = false>
; __device__ __forceinline__ void gemm_phase(PG8_LAS unsigned char* lds, const Gemm g, const Sched& S, const Epi& E) {
;     ...
;         if (!has_next) break;
; #pragma unroll
;         for (int a = 0; a < 2; ++a)
; #pragma unroll
;             for (int b = 0; b < 2; ++b)
; #pragma unroll
;                 for (int m = 0; m < 4; ++m)
; #pragma unroll
;                     for (int n = 0; n < 2; ++n) acc[a][b][m][n] = (f32x4){0.f, 0.f, 0.f, 0.f};
;         cur = nxt; cA = nA; cB = nB; ++ui;
;         if constexpr (ALIGN_EPI) { if (wr == 1) PG8_BAR; }
;     __device__ __forceinline__ void operator()(const f32x4 (&acc)[2][2][4][2], const Unit& u, int wr, int wc, int fr, int fq) const {
;     ...
;                 for (int bj = 0; bj < 2; ++bj) {
;                     const int col = col0 + bj * 128;
;                     const u32x4 g = *(const u32x4*)(P + row * PS + C_GATE + 4096 + col);
;                     f32x4 v0 = acc[ai][bj][m][0], v1 = acc[ai][bj][m][1];
;                     v0[0] *= fmaxf(bflo(g.x), 1e-20f); v0[1] *= fmaxf(bfhi(g.x), 1e-20f); v0[2] *= fmaxf(bflo(g.y), 1e-20f); v0[3] *= fmaxf(bfhi(g.y), 1e-20f);
;                     v1[0] *= fmaxf(bflo(g.z), 1e-20f); v1[1] *= fmaxf(bfhi(g.z), 1e-20f); v1[2] *= fmaxf(bflo(g.w), 1e-20f); v1[3] *= fmaxf(bfhi(g.w), 1e-20f);
;                     u32x4 w; w.x = pk2(v0[0], v0[1]); w.y = pk2(v0[2], v0[3]); w.z = pk2(v1[0], v1[1]); w.w = pk2(v1[2], v1[3]);
;                     *(u32x4*)(Yb + row * DM + col) = w;
	v_lshlrev_b32_e32 v246, 16, v214
	v_and_b32_e32 v247, 0xffff0000, v214
	v_lshlrev_b32_e32 v248, 16, v215
	v_and_b32_e32 v249, 0xffff0000, v215
	v_max_f32_e32 v246, v246, v246
	v_max_f32_e32 v247, v247, v247
	v_max_f32_e32 v248, v248, v248
	v_max_f32_e32 v249, v249, v249
	v_max_f32_e32 v246, 0x1e3ce508, v246
	v_max_f32_e32 v247, 0x1e3ce508, v247
	v_max_f32_e32 v248, 0x1e3ce508, v248
	v_max_f32_e32 v249, 0x1e3ce508, v249
	v_pk_mul_f32 v[42:43], v[42:43], v[246:247]
	v_pk_mul_f32 v[44:45], v[44:45], v[248:249]
	v_lshlrev_b32_e32 v246, 16, v216
	v_and_b32_e32 v247, 0xffff0000, v216
	v_lshlrev_b32_e32 v248, 16, v217
	v_and_b32_e32 v249, 0xffff0000, v217
	v_max_f32_e32 v246, v246, v246
	v_max_f32_e32 v247, v247, v247
	v_max_f32_e32 v248, v248, v248
	v_max_f32_e32 v249, v249, v249
	v_max_f32_e32 v246, 0x1e3ce508, v246
	v_max_f32_e32 v247, 0x1e3ce508, v247
	v_max_f32_e32 v248, 0x1e3ce508, v248
	v_max_f32_e32 v249, 0x1e3ce508, v249
	v_pk_mul_f32 v[38:39], v[38:39], v[246:247]
	v_pk_mul_f32 v[40:41], v[40:41], v[248:249]
	v_cvt_pk_bf16_f32 v214, v42, v43
	v_cvt_pk_bf16_f32 v215, v44, v45
	v_cvt_pk_bf16_f32 v216, v38, v39
	v_cvt_pk_bf16_f32 v217, v40, v41
	global_store_dwordx4 v[162:163], v[214:217], off offset:256
	v_lshl_add_u64 v[162:163], v[162:163], 0, s[4:5]
	s_waitcnt vmcnt(15)
	v_lshlrev_b32_e32 v246, 16, v218
	v_and_b32_e32 v247, 0xffff0000, v218
	v_lshlrev_b32_e32 v248, 16, v219
	v_and_b32_e32 v249, 0xffff0000, v219
	v_max_f32_e32 v246, v246, v246
	v_max_f32_e32 v247, v247, v247
	v_max_f32_e32 v248, v248, v248
	v_max_f32_e32 v249, v249, v249
	v_max_f32_e32 v246, 0x1e3ce508, v246
	v_max_f32_e32 v247, 0x1e3ce508, v247
	v_max_f32_e32 v248, 0x1e3ce508, v248
	v_max_f32_e32 v249, 0x1e3ce508, v249
	v_pk_mul_f32 v[28:29], v[28:29], v[246:247]
	v_pk_mul_f32 v[30:31], v[30:31], v[248:249]
	v_lshlrev_b32_e32 v246, 16, v220
	v_and_b32_e32 v247, 0xffff0000, v220
	v_lshlrev_b32_e32 v248, 16, v221
	v_and_b32_e32 v249, 0xffff0000, v221
	v_max_f32_e32 v246, v246, v246
	v_max_f32_e32 v247, v247, v247
	v_max_f32_e32 v248, v248, v248
	v_max_f32_e32 v249, v249, v249
	v_max_f32_e32 v246, 0x1e3ce508, v246
	v_max_f32_e32 v247, 0x1e3ce508, v247
	v_max_f32_e32 v248, 0x1e3ce508, v248
	v_max_f32_e32 v249, 0x1e3ce508, v249
	v_pk_mul_f32 v[24:25], v[24:25], v[246:247]
	v_pk_mul_f32 v[26:27], v[26:27], v[248:249]
	v_cvt_pk_bf16_f32 v218, v28, v29
	v_cvt_pk_bf16_f32 v219, v30, v31
	v_cvt_pk_bf16_f32 v220, v24, v25
	v_cvt_pk_bf16_f32 v221, v26, v27
	global_store_dwordx4 v[162:163], v[218:221], off
	s_waitcnt vmcnt(15)
	v_lshlrev_b32_e32 v246, 16, v222
	v_and_b32_e32 v247, 0xffff0000, v222
	v_lshlrev_b32_e32 v248, 16, v223
	v_and_b32_e32 v249, 0xffff0000, v223
	v_max_f32_e32 v246, v246, v246
	v_max_f32_e32 v247, v247, v247
	v_max_f32_e32 v248, v248, v248
	v_max_f32_e32 v249, v249, v249
	v_max_f32_e32 v246, 0x1e3ce508, v246
	v_max_f32_e32 v247, 0x1e3ce508, v247
	v_max_f32_e32 v248, 0x1e3ce508, v248
	v_max_f32_e32 v249, 0x1e3ce508, v249
	v_pk_mul_f32 v[20:21], v[20:21], v[246:247]
	v_pk_mul_f32 v[22:23], v[22:23], v[248:249]
	v_lshlrev_b32_e32 v246, 16, v224
	v_and_b32_e32 v247, 0xffff0000, v224
	v_lshlrev_b32_e32 v248, 16, v225
	v_and_b32_e32 v249, 0xffff0000, v225
	v_max_f32_e32 v246, v246, v246
	v_max_f32_e32 v247, v247, v247
	v_max_f32_e32 v248, v248, v248
	v_max_f32_e32 v249, v249, v249
	v_max_f32_e32 v246, 0x1e3ce508, v246
	v_max_f32_e32 v247, 0x1e3ce508, v247
	v_max_f32_e32 v248, 0x1e3ce508, v248
	v_max_f32_e32 v249, 0x1e3ce508, v249
	v_pk_mul_f32 v[16:17], v[16:17], v[246:247]
	v_pk_mul_f32 v[18:19], v[18:19], v[248:249]
	v_cvt_pk_bf16_f32 v222, v20, v21
	v_cvt_pk_bf16_f32 v223, v22, v23
	v_cvt_pk_bf16_f32 v224, v16, v17
	v_cvt_pk_bf16_f32 v225, v18, v19
	global_store_dwordx4 v[162:163], v[222:225], off offset:256
	v_lshl_add_u64 v[162:163], v[162:163], 0, s[4:5]
	s_waitcnt vmcnt(15)
	v_lshlrev_b32_e32 v246, 16, v226
	v_and_b32_e32 v247, 0xffff0000, v226
	v_lshlrev_b32_e32 v248, 16, v227
	v_and_b32_e32 v249, 0xffff0000, v227
	v_max_f32_e32 v246, v246, v246
	v_max_f32_e32 v247, v247, v247
	v_max_f32_e32 v248, v248, v248
	v_max_f32_e32 v249, v249, v249
	v_max_f32_e32 v246, 0x1e3ce508, v246
	v_max_f32_e32 v247, 0x1e3ce508, v247
	v_max_f32_e32 v248, 0x1e3ce508, v248
	v_max_f32_e32 v249, 0x1e3ce508, v249
	v_pk_mul_f32 v[12:13], v[12:13], v[246:247]
	v_pk_mul_f32 v[14:15], v[14:15], v[248:249]
	v_lshlrev_b32_e32 v246, 16, v228
	v_and_b32_e32 v247, 0xffff0000, v228
	v_lshlrev_b32_e32 v248, 16, v229
	v_and_b32_e32 v249, 0xffff0000, v229
	v_max_f32_e32 v246, v246, v246
	v_max_f32_e32 v247, v247, v247
	v_max_f32_e32 v248, v248, v248
	v_max_f32_e32 v249, v249, v249
	v_max_f32_e32 v246, 0x1e3ce508, v246
	v_max_f32_e32 v247, 0x1e3ce508, v247
	v_max_f32_e32 v248, 0x1e3ce508, v248
	v_max_f32_e32 v249, 0x1e3ce508, v249
	v_pk_mul_f32 v[8:9], v[8:9], v[246:247]
	v_pk_mul_f32 v[10:11], v[10:11], v[248:249]
	v_cvt_pk_bf16_f32 v226, v12, v13
	v_cvt_pk_bf16_f32 v227, v14, v15
	v_cvt_pk_bf16_f32 v228, v8, v9
	v_cvt_pk_bf16_f32 v229, v10, v11
	global_store_dwordx4 v[162:163], v[226:229], off
	s_waitcnt vmcnt(15)
	v_lshlrev_b32_e32 v246, 16, v230
	v_and_b32_e32 v247, 0xffff0000, v230
	v_lshlrev_b32_e32 v248, 16, v231
	v_and_b32_e32 v249, 0xffff0000, v231
	v_max_f32_e32 v246, v246, v246
	v_max_f32_e32 v247, v247, v247
	v_max_f32_e32 v248, v248, v248
	v_max_f32_e32 v249, v249, v249
	v_max_f32_e32 v246, 0x1e3ce508, v246
	v_max_f32_e32 v247, 0x1e3ce508, v247
	v_max_f32_e32 v248, 0x1e3ce508, v248
	v_max_f32_e32 v249, 0x1e3ce508, v249
	v_pk_mul_f32 v[4:5], v[4:5], v[246:247]
	v_pk_mul_f32 v[6:7], v[6:7], v[248:249]
	v_lshlrev_b32_e32 v246, 16, v232
	v_and_b32_e32 v247, 0xffff0000, v232
	v_lshlrev_b32_e32 v248, 16, v233
	v_and_b32_e32 v249, 0xffff0000, v233
	v_max_f32_e32 v246, v246, v246
	v_max_f32_e32 v247, v247, v247
	v_max_f32_e32 v248, v248, v248
	v_max_f32_e32 v249, v249, v249
	v_max_f32_e32 v246, 0x1e3ce508, v246
	v_max_f32_e32 v247, 0x1e3ce508, v247
	v_max_f32_e32 v248, 0x1e3ce508, v248
	v_max_f32_e32 v249, 0x1e3ce508, v249
	v_pk_mul_f32 v[0:1], v[0:1], v[246:247]
	v_pk_mul_f32 v[2:3], v[2:3], v[248:249]
	v_cvt_pk_bf16_f32 v230, v4, v5
	v_cvt_pk_bf16_f32 v231, v6, v7
	v_cvt_pk_bf16_f32 v232, v0, v1
	v_cvt_pk_bf16_f32 v233, v2, v3
	global_store_dwordx4 v[162:163], v[230:233], off offset:256
	s_andn2_b64 vcc, exec, s[56:57]
	s_mov_b64 s[0:1], -1
	s_cbranch_vccnz .LBB0_742
	s_andn2_b64 vcc, exec, s[38:39]
	s_cbranch_vccnz .LBB0_741
	s_barrier
	s_branch .LBB0_741
